# G3 K-loop: first four MFMAs of each super-phase issued before the load-segment barrier (matrix-pipe work queued across the hand-off)
# speedup vs baseline: 1.0049x; 1.0049x over previous
.LBB0_980:
	ds_read_b128 v[144:147], v151
	ds_read_b128 v[156:159], v151 offset:1024
	ds_read_b128 v[160:163], v151 offset:2048
	ds_read_b128 v[164:167], v151 offset:3072
	ds_read_b128 v[168:171], v152
	ds_read_b128 v[172:175], v152 offset:1024
	ds_read_b128 v[176:179], v152 offset:2048
	ds_read_b128 v[180:183], v152 offset:3072
	s_add_u32 s34, s22, 0xfffc0080
	s_addc_u32 s35, s23, -1
	s_cmp_eq_u32 s55, 12
	s_cselect_b32 s37, s15, s35
	s_cselect_b32 s36, s51, s34
	s_cselect_b32 s35, s13, s54
	s_cselect_b32 s34, s52, s53
	v_lshl_add_u64 v[218:219], s[22:23], 0, v[136:137]
	s_add_i32 m0, s21, 0xc000
	ds_read_b128 v[184:187], v153
	ds_read_b128 v[190:193], v153 offset:1024
	ds_read_b128 v[194:197], v153 offset:2048
	ds_read_b128 v[198:201], v153 offset:3072
	ds_read_b128 v[202:205], v153 offset:4096
	ds_read_b128 v[206:209], v153 offset:5120
	ds_read_b128 v[210:213], v153 offset:6144
	ds_read_b128 v[214:217], v153 offset:7168
	global_load_lds_dwordx4 v[218:219], off
	v_lshl_add_u64 v[218:219], s[22:23], 0, v[138:139]
	s_add_i32 m0, s21, 0xe000
	s_nop 0
	global_load_lds_dwordx4 v[218:219], off
	s_waitcnt vmcnt(8)
	s_waitcnt lgkmcnt(0)
	v_mfma_f32_16x16x32_bf16 v[116:119], v[144:147], v[184:187], v[116:119]
	v_mfma_f32_16x16x32_bf16 v[112:115], v[160:163], v[184:187], v[112:115]
	v_mfma_f32_16x16x32_bf16 v[104:107], v[144:147], v[194:197], v[104:107]
	v_mfma_f32_16x16x32_bf16 v[96:99], v[160:163], v[194:197], v[96:99]
	s_barrier
	s_setprio 1
	v_mfma_f32_16x16x32_bf16 v[88:91], v[144:147], v[202:205], v[88:91]
	v_mfma_f32_16x16x32_bf16 v[80:83], v[160:163], v[202:205], v[80:83]
	v_mfma_f32_16x16x32_bf16 v[72:75], v[144:147], v[210:213], v[72:75]
	v_mfma_f32_16x16x32_bf16 v[68:71], v[160:163], v[210:213], v[68:71]
	v_mfma_f32_16x16x32_bf16 v[116:119], v[156:159], v[190:193], v[116:119]
	v_mfma_f32_16x16x32_bf16 v[112:115], v[164:167], v[190:193], v[112:115]
	v_mfma_f32_16x16x32_bf16 v[104:107], v[156:159], v[198:201], v[104:107]
	v_mfma_f32_16x16x32_bf16 v[96:99], v[164:167], v[198:201], v[96:99]
	v_mfma_f32_16x16x32_bf16 v[88:91], v[156:159], v[206:209], v[88:91]
	v_mfma_f32_16x16x32_bf16 v[80:83], v[164:167], v[206:209], v[80:83]
	v_mfma_f32_16x16x32_bf16 v[72:75], v[156:159], v[214:217], v[72:75]
	v_mfma_f32_16x16x32_bf16 v[68:71], v[164:167], v[214:217], v[68:71]
	s_setprio 0
	s_setprio 1
	v_mfma_f32_16x16x32_bf16 v[124:127], v[168:171], v[184:187], v[124:127]
	v_mfma_f32_16x16x32_bf16 v[120:123], v[176:179], v[184:187], v[120:123]
	v_mfma_f32_16x16x32_bf16 v[108:111], v[168:171], v[194:197], v[108:111]
	v_mfma_f32_16x16x32_bf16 v[100:103], v[176:179], v[194:197], v[100:103]
	v_mfma_f32_16x16x32_bf16 v[92:95], v[168:171], v[202:205], v[92:95]
	v_mfma_f32_16x16x32_bf16 v[84:87], v[176:179], v[202:205], v[84:87]
	v_mfma_f32_16x16x32_bf16 v[76:79], v[168:171], v[210:213], v[76:79]
	v_mfma_f32_16x16x32_bf16 v[64:67], v[176:179], v[210:213], v[64:67]
	v_mfma_f32_16x16x32_bf16 v[124:127], v[172:175], v[190:193], v[124:127]
	v_mfma_f32_16x16x32_bf16 v[120:123], v[180:183], v[190:193], v[120:123]
	v_mfma_f32_16x16x32_bf16 v[108:111], v[172:175], v[198:201], v[108:111]
	v_mfma_f32_16x16x32_bf16 v[100:103], v[180:183], v[198:201], v[100:103]
	v_mfma_f32_16x16x32_bf16 v[92:95], v[172:175], v[206:209], v[92:95]
	v_mfma_f32_16x16x32_bf16 v[84:87], v[180:183], v[206:209], v[84:87]
	v_mfma_f32_16x16x32_bf16 v[76:79], v[172:175], v[214:217], v[76:79]
	v_mfma_f32_16x16x32_bf16 v[64:67], v[180:183], v[214:217], v[64:67]
	s_setprio 0
	s_barrier
	s_add_i32 s56, s47, s38
	v_lshl_add_u64 v[218:219], s[34:35], 0, v[130:131]
	s_mov_b32 m0, s56
	ds_read_b128 v[184:187], v153 offset:16384
	ds_read_b128 v[190:193], v153 offset:17408
	ds_read_b128 v[194:197], v153 offset:18432
	ds_read_b128 v[198:201], v153 offset:19456
	ds_read_b128 v[202:205], v153 offset:20480
	ds_read_b128 v[206:209], v153 offset:21504
	ds_read_b128 v[210:213], v153 offset:22528
	ds_read_b128 v[214:217], v153 offset:23552
	global_load_lds_dwordx4 v[218:219], off
	s_add_i32 m0, s56, 0x2000
	s_add_u32 s56, s34, 0x40000
	v_lshl_add_u64 v[220:221], s[34:35], 0, v[134:135]
	s_addc_u32 s57, s35, 0
	s_add_i32 s58, s48, s38
	global_load_lds_dwordx4 v[220:221], off
	v_lshl_add_u64 v[222:223], s[56:57], 0, v[130:131]
	s_mov_b32 m0, s58
	v_lshl_add_u64 v[224:225], s[36:37], 0, v[132:133]
	global_load_lds_dwordx4 v[222:223], off
	v_lshl_add_u64 v[222:223], s[56:57], 0, v[134:135]
	s_add_i32 m0, s58, 0x2000
	s_nop 0
	global_load_lds_dwordx4 v[222:223], off
	v_lshl_add_u64 v[222:223], s[36:37], 0, v[128:129]
	s_mov_b32 m0, s21
	s_nop 0
	global_load_lds_dwordx4 v[222:223], off
	s_mov_b32 m0, s39
	s_nop 0
	global_load_lds_dwordx4 v[224:225], off
	s_waitcnt vmcnt(8)
	s_waitcnt lgkmcnt(0)
	v_mfma_f32_16x16x32_bf16 v[56:59], v[144:147], v[184:187], v[56:59]
	v_mfma_f32_16x16x32_bf16 v[48:51], v[160:163], v[184:187], v[48:51]
	v_mfma_f32_16x16x32_bf16 v[40:43], v[144:147], v[194:197], v[40:43]
	v_mfma_f32_16x16x32_bf16 v[32:35], v[160:163], v[194:197], v[32:35]
	s_barrier
	s_setprio 1
	v_mfma_f32_16x16x32_bf16 v[24:27], v[144:147], v[202:205], v[24:27]
	v_mfma_f32_16x16x32_bf16 v[16:19], v[160:163], v[202:205], v[16:19]
	v_mfma_f32_16x16x32_bf16 v[8:11], v[144:147], v[210:213], v[8:11]
	v_mfma_f32_16x16x32_bf16 v[0:3], v[160:163], v[210:213], v[0:3]
	v_mfma_f32_16x16x32_bf16 v[56:59], v[156:159], v[190:193], v[56:59]
	v_mfma_f32_16x16x32_bf16 v[48:51], v[164:167], v[190:193], v[48:51]
	v_mfma_f32_16x16x32_bf16 v[40:43], v[156:159], v[198:201], v[40:43]
	v_mfma_f32_16x16x32_bf16 v[32:35], v[164:167], v[198:201], v[32:35]
	v_mfma_f32_16x16x32_bf16 v[24:27], v[156:159], v[206:209], v[24:27]
	v_mfma_f32_16x16x32_bf16 v[16:19], v[164:167], v[206:209], v[16:19]
	v_mfma_f32_16x16x32_bf16 v[8:11], v[156:159], v[214:217], v[8:11]
	v_mfma_f32_16x16x32_bf16 v[0:3], v[164:167], v[214:217], v[0:3]
	s_setprio 0
	s_setprio 1
	v_mfma_f32_16x16x32_bf16 v[60:63], v[168:171], v[184:187], v[60:63]
	v_mfma_f32_16x16x32_bf16 v[52:55], v[176:179], v[184:187], v[52:55]
	v_mfma_f32_16x16x32_bf16 v[44:47], v[168:171], v[194:197], v[44:47]
	v_mfma_f32_16x16x32_bf16 v[36:39], v[176:179], v[194:197], v[36:39]
	v_mfma_f32_16x16x32_bf16 v[28:31], v[168:171], v[202:205], v[28:31]
	v_mfma_f32_16x16x32_bf16 v[20:23], v[176:179], v[202:205], v[20:23]
	v_mfma_f32_16x16x32_bf16 v[12:15], v[168:171], v[210:213], v[12:15]
	v_mfma_f32_16x16x32_bf16 v[4:7], v[176:179], v[210:213], v[4:7]
	v_mfma_f32_16x16x32_bf16 v[60:63], v[172:175], v[190:193], v[60:63]
	v_mfma_f32_16x16x32_bf16 v[52:55], v[180:183], v[190:193], v[52:55]
	v_mfma_f32_16x16x32_bf16 v[44:47], v[172:175], v[198:201], v[44:47]
	v_mfma_f32_16x16x32_bf16 v[36:39], v[180:183], v[198:201], v[36:39]
	v_mfma_f32_16x16x32_bf16 v[28:31], v[172:175], v[206:209], v[28:31]
	v_mfma_f32_16x16x32_bf16 v[20:23], v[180:183], v[206:209], v[20:23]
	v_mfma_f32_16x16x32_bf16 v[12:15], v[172:175], v[214:217], v[12:15]
	v_mfma_f32_16x16x32_bf16 v[4:7], v[180:183], v[214:217], v[4:7]
	s_setprio 0
	s_barrier
	s_add_i32 s56, 0, 0x18000
	v_add_u32_e32 v155, s56, v149
	s_add_i32 s57, 0, 0x1c000
	ds_read_b128 v[144:147], v155
	ds_read_b128 v[156:159], v155 offset:1024
	ds_read_b128 v[160:163], v155 offset:2048
	ds_read_b128 v[164:167], v155 offset:3072
	v_add_u32_e32 v155, s57, v149
	ds_read_b128 v[168:171], v155
	ds_read_b128 v[172:175], v155 offset:1024
	ds_read_b128 v[176:179], v155 offset:2048
	ds_read_b128 v[180:183], v155 offset:3072
	s_add_u32 s36, s36, 0x40000
	s_addc_u32 s37, s37, 0
	s_mov_b32 m0, s40
	v_lshl_add_u64 v[226:227], s[36:37], 0, v[128:129]
	ds_read_b128 v[184:187], v153 offset:32768
	ds_read_b128 v[190:193], v153 offset:33792
	ds_read_b128 v[194:197], v153 offset:34816
	ds_read_b128 v[198:201], v153 offset:35840
	ds_read_b128 v[202:205], v153 offset:36864
	ds_read_b128 v[206:209], v153 offset:37888
	ds_read_b128 v[210:213], v153 offset:38912
	ds_read_b128 v[214:217], v153 offset:39936
	global_load_lds_dwordx4 v[226:227], off
	v_lshl_add_u64 v[226:227], s[36:37], 0, v[132:133]
	s_mov_b32 m0, s41
	s_nop 0
	global_load_lds_dwordx4 v[226:227], off
	s_waitcnt vmcnt(8)
	s_waitcnt lgkmcnt(0)
	v_mfma_f32_16x16x32_bf16 v[116:119], v[144:147], v[184:187], v[116:119]
	v_mfma_f32_16x16x32_bf16 v[112:115], v[160:163], v[184:187], v[112:115]
	v_mfma_f32_16x16x32_bf16 v[104:107], v[144:147], v[194:197], v[104:107]
	v_mfma_f32_16x16x32_bf16 v[96:99], v[160:163], v[194:197], v[96:99]
	s_barrier
	s_setprio 1
	v_mfma_f32_16x16x32_bf16 v[88:91], v[144:147], v[202:205], v[88:91]
	v_mfma_f32_16x16x32_bf16 v[80:83], v[160:163], v[202:205], v[80:83]
	v_mfma_f32_16x16x32_bf16 v[72:75], v[144:147], v[210:213], v[72:75]
	v_mfma_f32_16x16x32_bf16 v[68:71], v[160:163], v[210:213], v[68:71]
	v_mfma_f32_16x16x32_bf16 v[116:119], v[156:159], v[190:193], v[116:119]
	v_mfma_f32_16x16x32_bf16 v[112:115], v[164:167], v[190:193], v[112:115]
	v_mfma_f32_16x16x32_bf16 v[104:107], v[156:159], v[198:201], v[104:107]
	v_mfma_f32_16x16x32_bf16 v[96:99], v[164:167], v[198:201], v[96:99]
	v_mfma_f32_16x16x32_bf16 v[88:91], v[156:159], v[206:209], v[88:91]
	v_mfma_f32_16x16x32_bf16 v[80:83], v[164:167], v[206:209], v[80:83]
	v_mfma_f32_16x16x32_bf16 v[72:75], v[156:159], v[214:217], v[72:75]
	v_mfma_f32_16x16x32_bf16 v[68:71], v[164:167], v[214:217], v[68:71]
	s_setprio 0
	s_setprio 1
	v_mfma_f32_16x16x32_bf16 v[124:127], v[168:171], v[184:187], v[124:127]
	v_mfma_f32_16x16x32_bf16 v[120:123], v[176:179], v[184:187], v[120:123]
	v_mfma_f32_16x16x32_bf16 v[108:111], v[168:171], v[194:197], v[108:111]
	v_mfma_f32_16x16x32_bf16 v[100:103], v[176:179], v[194:197], v[100:103]
	v_mfma_f32_16x16x32_bf16 v[92:95], v[168:171], v[202:205], v[92:95]
	v_mfma_f32_16x16x32_bf16 v[84:87], v[176:179], v[202:205], v[84:87]
	v_mfma_f32_16x16x32_bf16 v[76:79], v[168:171], v[210:213], v[76:79]
	v_mfma_f32_16x16x32_bf16 v[64:67], v[176:179], v[210:213], v[64:67]
	v_mfma_f32_16x16x32_bf16 v[124:127], v[172:175], v[190:193], v[124:127]
	v_mfma_f32_16x16x32_bf16 v[120:123], v[180:183], v[190:193], v[120:123]
	v_mfma_f32_16x16x32_bf16 v[108:111], v[172:175], v[198:201], v[108:111]
	v_mfma_f32_16x16x32_bf16 v[100:103], v[180:183], v[198:201], v[100:103]
	v_mfma_f32_16x16x32_bf16 v[92:95], v[172:175], v[206:209], v[92:95]
	v_mfma_f32_16x16x32_bf16 v[84:87], v[180:183], v[206:209], v[84:87]
	v_mfma_f32_16x16x32_bf16 v[76:79], v[172:175], v[214:217], v[76:79]
	v_mfma_f32_16x16x32_bf16 v[64:67], v[180:183], v[214:217], v[64:67]
	s_setprio 0
	s_barrier
	s_add_i32 s36, s56, s38
	v_lshl_add_u64 v[218:219], v[218:219], 0, s[8:9]
	s_mov_b32 m0, s36
	ds_read_b128 v[184:187], v153 offset:49152
	ds_read_b128 v[190:193], v153 offset:50176
	ds_read_b128 v[194:197], v153 offset:51200
	ds_read_b128 v[198:201], v153 offset:52224
	ds_read_b128 v[202:205], v153 offset:53248
	ds_read_b128 v[206:209], v153 offset:54272
	ds_read_b128 v[210:213], v153 offset:55296
	ds_read_b128 v[214:217], v153 offset:56320
	global_load_lds_dwordx4 v[218:219], off
	s_add_i32 m0, s36, 0x2000
	s_add_u32 s34, s34, 0x40080
	v_lshl_add_u64 v[218:219], v[220:221], 0, s[8:9]
	s_addc_u32 s35, s35, 0
	s_add_i32 s36, s57, s38
	global_load_lds_dwordx4 v[218:219], off
	v_lshl_add_u64 v[218:219], s[34:35], 0, v[130:131]
	s_mov_b32 m0, s36
	s_nop 0
	global_load_lds_dwordx4 v[218:219], off
	v_lshl_add_u64 v[218:219], s[34:35], 0, v[134:135]
	s_add_i32 m0, s36, 0x2000
	s_nop 0
	global_load_lds_dwordx4 v[218:219], off
	v_lshl_add_u64 v[218:219], v[222:223], 0, s[8:9]
	s_mov_b32 m0, s43
	s_nop 0
	global_load_lds_dwordx4 v[218:219], off
	v_lshl_add_u64 v[218:219], v[224:225], 0, s[8:9]
	s_mov_b32 m0, s44
	s_nop 0
	global_load_lds_dwordx4 v[218:219], off
	s_waitcnt vmcnt(8)
	s_waitcnt lgkmcnt(0)
	v_mfma_f32_16x16x32_bf16 v[56:59], v[144:147], v[184:187], v[56:59]
	v_mfma_f32_16x16x32_bf16 v[48:51], v[160:163], v[184:187], v[48:51]
	v_mfma_f32_16x16x32_bf16 v[40:43], v[144:147], v[194:197], v[40:43]
	v_mfma_f32_16x16x32_bf16 v[32:35], v[160:163], v[194:197], v[32:35]
	s_barrier
	s_setprio 1
	v_mfma_f32_16x16x32_bf16 v[24:27], v[144:147], v[202:205], v[24:27]
	v_mfma_f32_16x16x32_bf16 v[16:19], v[160:163], v[202:205], v[16:19]
	v_mfma_f32_16x16x32_bf16 v[8:11], v[144:147], v[210:213], v[8:11]
	v_mfma_f32_16x16x32_bf16 v[0:3], v[160:163], v[210:213], v[0:3]
	v_mfma_f32_16x16x32_bf16 v[56:59], v[156:159], v[190:193], v[56:59]
	v_mfma_f32_16x16x32_bf16 v[48:51], v[164:167], v[190:193], v[48:51]
	v_mfma_f32_16x16x32_bf16 v[40:43], v[156:159], v[198:201], v[40:43]
	v_mfma_f32_16x16x32_bf16 v[32:35], v[164:167], v[198:201], v[32:35]
	v_mfma_f32_16x16x32_bf16 v[24:27], v[156:159], v[206:209], v[24:27]
	v_mfma_f32_16x16x32_bf16 v[16:19], v[164:167], v[206:209], v[16:19]
	v_mfma_f32_16x16x32_bf16 v[8:11], v[156:159], v[214:217], v[8:11]
	v_mfma_f32_16x16x32_bf16 v[0:3], v[164:167], v[214:217], v[0:3]
	s_setprio 0
	s_setprio 1
	v_mfma_f32_16x16x32_bf16 v[60:63], v[168:171], v[184:187], v[60:63]
	v_mfma_f32_16x16x32_bf16 v[52:55], v[176:179], v[184:187], v[52:55]
	v_mfma_f32_16x16x32_bf16 v[44:47], v[168:171], v[194:197], v[44:47]
	v_mfma_f32_16x16x32_bf16 v[36:39], v[176:179], v[194:197], v[36:39]
	v_mfma_f32_16x16x32_bf16 v[28:31], v[168:171], v[202:205], v[28:31]
	v_mfma_f32_16x16x32_bf16 v[20:23], v[176:179], v[202:205], v[20:23]
	v_mfma_f32_16x16x32_bf16 v[12:15], v[168:171], v[210:213], v[12:15]
	v_mfma_f32_16x16x32_bf16 v[4:7], v[176:179], v[210:213], v[4:7]
	v_mfma_f32_16x16x32_bf16 v[60:63], v[172:175], v[190:193], v[60:63]
	v_mfma_f32_16x16x32_bf16 v[52:55], v[180:183], v[190:193], v[52:55]
	v_mfma_f32_16x16x32_bf16 v[44:47], v[172:175], v[198:201], v[44:47]
	v_mfma_f32_16x16x32_bf16 v[36:39], v[180:183], v[198:201], v[36:39]
	v_mfma_f32_16x16x32_bf16 v[28:31], v[172:175], v[206:209], v[28:31]
	v_mfma_f32_16x16x32_bf16 v[20:23], v[180:183], v[206:209], v[20:23]
	v_mfma_f32_16x16x32_bf16 v[12:15], v[172:175], v[214:217], v[12:15]
	v_mfma_f32_16x16x32_bf16 v[4:7], v[180:183], v[214:217], v[4:7]
	s_setprio 0
	s_barrier
	s_add_i32 s55, s55, 2
	s_add_u32 s22, s22, 0x100
	s_addc_u32 s23, s23, 0
	s_add_u32 s53, s53, 0x100
	s_addc_u32 s54, s54, 0
	s_cmp_gt_u32 s55, 13
	s_cbranch_scc0 .LBB0_980
	v_lshl_add_u32 v236, s20, 8, v148
	v_lshlrev_b32_e32 v236, 2, v236
	global_load_dword v228, v236, s[6:7]
	global_load_dword v229, v236, s[6:7] offset:64
	global_load_dword v230, v236, s[6:7] offset:128
	global_load_dword v231, v236, s[6:7] offset:192
	global_load_dword v232, v236, s[6:7] offset:512
	global_load_dword v233, v236, s[6:7] offset:576
	global_load_dword v234, v236, s[6:7] offset:640
	global_load_dword v235, v236, s[6:7] offset:704
	s_and_b64 vcc, exec, s[10:11]
	s_cbranch_vccz .LBB0_983
	s_barrier
